# FoX finalize: gated outputs staged in LDS and stored as 8 coalesced 16-byte-per-lane stores (was 16 stores of 8 bytes to 64 different rows each)
# speedup vs baseline: 1.0062x; 1.0038x over previous
; __device__ __forceinline__ float bflo(unsigned w) { return __uint_as_float(w << 16); }
; __device__ __forceinline__ float bfhi(unsigned w) { return __uint_as_float(w & 0xffff0000u); }
; __device__ __forceinline__ unsigned cvtpk(float lo, float hi) { unsigned r; asm volatile("v_cvt_pk_bf16_f32 %0, %1, %2" : "=v"(r) : "v"(lo), "v"(hi)); return r; }
; __device__ __forceinline__ float siluf_(float x) { return x * sigmoidf_(x); }
; __device__ __forceinline__ void item_fox(const Params& p, int l, int bl, int h, int qb, LAS unsigned char* lds) {
;     ...
;     { const float lt = lrun + __shfl_xor(lrun, 32), inv = 1.f / lt;
;       const size_t grow = (size_t)(bl * SEQ + qrow);
;       const u16* zp = p.proj + grow * NP + C_DZ + h * 128; u16* yp = p.ybuf + ((size_t)3 * MG + grow) * 512 + h * 128;
; #pragma unroll
;       for (int db = 0; db < 4; ++db)
; #pragma unroll
;           for (int r4 = 0; r4 < 4; ++r4) {
;               const int d0 = 32 * db + 8 * r4 + 4 * hi; const u32x2 z = *(const u32x2*)(zp + d0);
;               const float o0 = O[db][4 * r4] * inv * siluf_(bflo(z[0])), o1 = O[db][4 * r4 + 1] * inv * siluf_(bfhi(z[0])),
;                           o2 = O[db][4 * r4 + 2] * inv * siluf_(bflo(z[1])), o3 = O[db][4 * r4 + 3] * inv * siluf_(bfhi(z[1]));
;               u32x2 o = {cvtpk(o0, o1), cvtpk(o2, o3)}; *(u32x2*)(yp + d0) = o; } }
.LBB0_1012:
	v_and_b32_e32 v214, 31, v206
	v_lshrrev_b32_e32 v215, 4, v206
	v_sub_u32_e32 v212, v161, v214
	v_add_u32_e32 v212, v212, v215
	v_lshl_add_u32 v212, s37, 12, v212
	v_lshlrev_b32_e32 v212, 10, v212
	v_and_b32_e32 v213, 15, v206
	v_lshl_add_u32 v212, v213, 4, v212
	v_lshrrev_b32_e32 v216, 6, v198
	v_mul_u32_u24_e32 v217, 0x2200, v216
	v_cmp_lt_u32_e32 vcc, 3, v216
	v_mov_b32_e32 v216, 0xd800
	s_nop 0
	v_cndmask_b32_e32 v216, 0, v216, vcc
	v_add_u32_e32 v217, v217, v216
	v_mul_u32_u24_e32 v216, 0x110, v215
	v_lshl_add_u32 v215, v213, 4, v216
	v_add_u32_e32 v215, v215, v217
	v_mul_u32_u24_e32 v214, 0x110, v214
	v_lshrrev_b32_e32 v216, 5, v206
	v_lshl_add_u32 v214, v216, 3, v214
	v_add_u32_e32 v214, v214, v217
	v_mov_b32_e32 v213, 0
	v_lshl_add_u64 v[212:213], s[16:17], 0, v[212:213]
	v_cmp_lt_i32_e32 vcc, v163, v173
	s_lshl_b32 s30, s0, 1
	s_add_u32 s20, s30, 0x3000000
	s_addc_u32 s21, 0, 0
	v_lshl_add_u64 v[212:213], v[212:213], 0, s[20:21]
	s_mov_b64 s[0:1], 0x3400
	v_cndmask_b32_e32 v0, v206, v163, vcc
	v_lshlrev_b32_e32 v0, 2, v0
	ds_bpermute_b32 v0, v0, v187
	v_mov_b32_e32 v10, v64
	s_waitcnt lgkmcnt(0)
	v_add_f32_e32 v0, v187, v0
	v_div_scale_f32 v2, s[20:21], v0, v0, 1.0
	v_rcp_f32_e32 v3, v2
	s_nop 0
	v_fma_f32 v4, -v2, v3, 1.0
	v_fmac_f32_e32 v3, v4, v3
	v_div_scale_f32 v4, vcc, 1.0, v0, 1.0
	v_mul_f32_e32 v5, v4, v3
	v_fma_f32 v6, -v2, v5, v4
	v_fmac_f32_e32 v5, v6, v3
	v_fma_f32 v2, -v2, v5, v4
	v_lshl_add_u32 v4, s37, 12, v161
	v_mov_b64_e32 v[6:7], s[14:15]
	v_div_fmas_f32 v2, v2, v3, v5
	v_ashrrev_i32_e32 v5, 31, v4
	v_mad_i64_i32 v[6:7], s[20:21], v4, s33, v[6:7]
	v_lshl_add_u64 v[8:9], v[6:7], 0, s[30:31]
	v_lshlrev_b64 v[4:5], 10, v[4:5]
	v_mov_b32_e32 v161, v1
	v_lshl_add_u64 v[4:5], s[16:17], 0, v[4:5]
	v_lshl_add_u64 v[8:9], v[8:9], 0, v[160:161]
	v_lshl_add_u64 v[6:7], v[4:5], 0, s[30:31]
	v_lshl_add_u64 v[4:5], v[8:9], 0, s[0:1]
	global_load_dwordx2 v[112:113], v[4:5], off
	global_load_dwordx2 v[114:115], v[4:5], off offset:16
	global_load_dwordx2 v[116:117], v[4:5], off offset:32
	global_load_dwordx2 v[118:119], v[4:5], off offset:48
	global_load_dwordx2 v[120:121], v[4:5], off offset:64
	global_load_dwordx2 v[122:123], v[4:5], off offset:80
	global_load_dwordx2 v[124:125], v[4:5], off offset:96
	global_load_dwordx2 v[126:127], v[4:5], off offset:112
	global_load_dwordx2 v[128:129], v[4:5], off offset:128
	global_load_dwordx2 v[130:131], v[4:5], off offset:144
	global_load_dwordx2 v[132:133], v[4:5], off offset:160
	global_load_dwordx2 v[134:135], v[4:5], off offset:176
	global_load_dwordx2 v[136:137], v[4:5], off offset:192
	global_load_dwordx2 v[138:139], v[4:5], off offset:208
	global_load_dwordx2 v[140:141], v[4:5], off offset:224
	global_load_dwordx2 v[142:143], v[4:5], off offset:240
	s_movk_i32 s0, 0x3000
	v_add_co_u32_e32 v8, vcc, s0, v8
	v_div_fixup_f32 v2, v2, v0, 1.0
	s_nop 0
	v_addc_co_u32_e32 v9, vcc, 0, v9, vcc
	s_waitcnt vmcnt(15)
	v_mov_b32_e32 v8, v112
	v_mov_b32_e32 v9, v113
	s_mov_b64 s[0:1], 0x3000000
	v_lshlrev_b32_e32 v3, 16, v8
	v_mul_f32_e32 v0, 0xbfb8aa3b, v3
	v_exp_f32_e32 v0, v0
	s_nop 0
	v_add_f32_e32 v0, 1.0, v0
	v_rcp_f32_e32 v11, v0
	s_nop 0
	v_pk_mul_f32 v[10:11], v[10:11], v[2:3]
	v_and_b32_e32 v3, 0xffff0000, v8
	v_mul_f32_e32 v8, 0xbfb8aa3b, v3
	v_exp_f32_e32 v8, v8
	v_mul_f32_e32 v0, v10, v11
	v_mov_b32_e32 v10, v65
	v_add_f32_e32 v8, 1.0, v8
	v_rcp_f32_e32 v11, v8
	s_nop 0
	v_pk_mul_f32 v[10:11], v[10:11], v[2:3]
	v_lshlrev_b32_e32 v3, 16, v9
	v_mul_f32_e32 v8, 0xbfb8aa3b, v3
	v_exp_f32_e32 v8, v8
	v_mul_f32_e32 v12, v10, v11
	v_mov_b32_e32 v10, v66
	v_add_f32_e32 v8, 1.0, v8
	v_rcp_f32_e32 v11, v8
	s_nop 0
	v_pk_mul_f32 v[10:11], v[10:11], v[2:3]
	v_and_b32_e32 v3, 0xffff0000, v9
	v_mul_f32_e32 v8, 0xbfb8aa3b, v3
	v_exp_f32_e32 v8, v8
	v_mul_f32_e32 v10, v10, v11
	v_add_f32_e32 v8, 1.0, v8
	v_rcp_f32_e32 v9, v8
	v_mov_b32_e32 v8, v67
	v_pk_mul_f32 v[8:9], v[8:9], v[2:3]
	s_nop 0
	v_mul_f32_e32 v3, v8, v9
	v_cvt_pk_bf16_f32 v8, v0, v12
	v_cvt_pk_bf16_f32 v9, v10, v3
	v_lshl_add_u64 v[10:11], v[6:7], 0, v[160:161]
	v_lshl_add_u64 v[6:7], v[10:11], 0, s[0:1]
	s_mov_b32 s0, 0x3000000
	v_add_co_u32_e32 v10, vcc, s0, v10
	s_mov_b64 s[0:1], -1
	s_nop 0
	v_addc_co_u32_e32 v11, vcc, 0, v11, vcc
	ds_write_b64 v214, v[8:9]
	s_waitcnt vmcnt(14)
	v_mov_b32_e32 v8, v114
	v_mov_b32_e32 v9, v115
	v_mov_b32_e32 v10, v68
	v_lshlrev_b32_e32 v3, 16, v8
	v_mul_f32_e32 v0, 0xbfb8aa3b, v3
	v_exp_f32_e32 v0, v0
	s_nop 0
	v_add_f32_e32 v0, 1.0, v0
	v_rcp_f32_e32 v11, v0
	s_nop 0
	v_pk_mul_f32 v[10:11], v[10:11], v[2:3]
	v_and_b32_e32 v3, 0xffff0000, v8
	v_mul_f32_e32 v8, 0xbfb8aa3b, v3
	v_exp_f32_e32 v8, v8
	v_mul_f32_e32 v0, v10, v11
	v_mov_b32_e32 v10, v69
	v_add_f32_e32 v8, 1.0, v8
	v_rcp_f32_e32 v11, v8
	s_nop 0
	v_pk_mul_f32 v[10:11], v[10:11], v[2:3]
	v_lshlrev_b32_e32 v3, 16, v9
	v_mul_f32_e32 v8, 0xbfb8aa3b, v3
	v_exp_f32_e32 v8, v8
	v_mul_f32_e32 v12, v10, v11
	v_mov_b32_e32 v10, v70
	v_add_f32_e32 v8, 1.0, v8
	v_rcp_f32_e32 v11, v8
	s_nop 0
	v_pk_mul_f32 v[10:11], v[10:11], v[2:3]
	v_and_b32_e32 v3, 0xffff0000, v9
	v_mul_f32_e32 v8, 0xbfb8aa3b, v3
	v_exp_f32_e32 v8, v8
	v_mul_f32_e32 v10, v10, v11
	v_add_f32_e32 v8, 1.0, v8
	v_rcp_f32_e32 v9, v8
	v_mov_b32_e32 v8, v71
	v_pk_mul_f32 v[8:9], v[8:9], v[2:3]
	s_nop 0
	v_mul_f32_e32 v3, v8, v9
	v_cvt_pk_bf16_f32 v8, v0, v12
	v_cvt_pk_bf16_f32 v9, v10, v3
	ds_write_b64 v214, v[8:9] offset:16
	s_waitcnt vmcnt(13)
; __device__ __forceinline__ float bflo(unsigned w) { return __uint_as_float(w << 16); }
; __device__ __forceinline__ float bfhi(unsigned w) { return __uint_as_float(w & 0xffff0000u); }
; __device__ __forceinline__ unsigned cvtpk(float lo, float hi) { unsigned r; asm volatile("v_cvt_pk_bf16_f32 %0, %1, %2" : "=v"(r) : "v"(lo), "v"(hi)); return r; }
; __device__ __forceinline__ float siluf_(float x) { return x * sigmoidf_(x); }
; __device__ __forceinline__ void item_fox(const Params& p, int l, int bl, int h, int qb, LAS unsigned char* lds) {
;     ...
;       for (int db = 0; db < 4; ++db)
; #pragma unroll
;           for (int r4 = 0; r4 < 4; ++r4) {
;               const int d0 = 32 * db + 8 * r4 + 4 * hi; const u32x2 z = *(const u32x2*)(zp + d0);
;               const float o0 = O[db][4 * r4] * inv * siluf_(bflo(z[0])), o1 = O[db][4 * r4 + 1] * inv * siluf_(bfhi(z[0])),
;                           o2 = O[db][4 * r4 + 2] * inv * siluf_(bflo(z[1])), o3 = O[db][4 * r4 + 3] * inv * siluf_(bfhi(z[1]));
;               u32x2 o = {cvtpk(o0, o1), cvtpk(o2, o3)}; *(u32x2*)(yp + d0) = o; } }
	v_mov_b32_e32 v8, v116
	v_mov_b32_e32 v9, v117
	v_mov_b32_e32 v10, v72
	v_lshlrev_b32_e32 v3, 16, v8
	v_mul_f32_e32 v0, 0xbfb8aa3b, v3
	v_exp_f32_e32 v0, v0
	s_nop 0
	v_add_f32_e32 v0, 1.0, v0
	v_rcp_f32_e32 v11, v0
	s_nop 0
	v_pk_mul_f32 v[10:11], v[10:11], v[2:3]
	v_and_b32_e32 v3, 0xffff0000, v8
	v_mul_f32_e32 v8, 0xbfb8aa3b, v3
	v_exp_f32_e32 v8, v8
	v_mul_f32_e32 v0, v10, v11
	v_mov_b32_e32 v10, v73
	v_add_f32_e32 v8, 1.0, v8
	v_rcp_f32_e32 v11, v8
	s_nop 0
	v_pk_mul_f32 v[10:11], v[10:11], v[2:3]
	v_lshlrev_b32_e32 v3, 16, v9
	v_mul_f32_e32 v8, 0xbfb8aa3b, v3
	v_exp_f32_e32 v8, v8
	v_mul_f32_e32 v12, v10, v11
	v_mov_b32_e32 v10, v74
	v_add_f32_e32 v8, 1.0, v8
	v_rcp_f32_e32 v11, v8
	s_nop 0
	v_pk_mul_f32 v[10:11], v[10:11], v[2:3]
	v_and_b32_e32 v3, 0xffff0000, v9
	v_mul_f32_e32 v8, 0xbfb8aa3b, v3
	v_exp_f32_e32 v8, v8
	v_mul_f32_e32 v10, v10, v11
	v_add_f32_e32 v8, 1.0, v8
	v_rcp_f32_e32 v9, v8
	v_mov_b32_e32 v8, v75
	v_pk_mul_f32 v[8:9], v[8:9], v[2:3]
	s_nop 0
	v_mul_f32_e32 v3, v8, v9
	v_cvt_pk_bf16_f32 v8, v0, v12
	v_cvt_pk_bf16_f32 v9, v10, v3
	ds_write_b64 v214, v[8:9] offset:32
	s_waitcnt vmcnt(12)
	v_mov_b32_e32 v8, v118
	v_mov_b32_e32 v9, v119
	v_mov_b32_e32 v10, v76
	v_lshlrev_b32_e32 v3, 16, v8
	v_mul_f32_e32 v0, 0xbfb8aa3b, v3
	v_exp_f32_e32 v0, v0
	s_nop 0
	v_add_f32_e32 v0, 1.0, v0
	v_rcp_f32_e32 v11, v0
	s_nop 0
	v_pk_mul_f32 v[10:11], v[10:11], v[2:3]
	v_and_b32_e32 v3, 0xffff0000, v8
	v_mul_f32_e32 v8, 0xbfb8aa3b, v3
	v_exp_f32_e32 v8, v8
	v_mul_f32_e32 v0, v10, v11
	v_mov_b32_e32 v10, v77
	v_add_f32_e32 v8, 1.0, v8
	v_rcp_f32_e32 v11, v8
	s_nop 0
	v_pk_mul_f32 v[10:11], v[10:11], v[2:3]
	v_lshlrev_b32_e32 v3, 16, v9
	v_mul_f32_e32 v8, 0xbfb8aa3b, v3
	v_exp_f32_e32 v8, v8
	v_mul_f32_e32 v12, v10, v11
	v_mov_b32_e32 v10, v78
	v_add_f32_e32 v8, 1.0, v8
	v_rcp_f32_e32 v11, v8
	s_nop 0
	v_pk_mul_f32 v[10:11], v[10:11], v[2:3]
	v_and_b32_e32 v3, 0xffff0000, v9
	v_mul_f32_e32 v8, 0xbfb8aa3b, v3
	v_exp_f32_e32 v8, v8
	v_mul_f32_e32 v10, v10, v11
	v_add_f32_e32 v8, 1.0, v8
	v_rcp_f32_e32 v9, v8
	v_mov_b32_e32 v8, v79
	v_pk_mul_f32 v[8:9], v[8:9], v[2:3]
	s_nop 0
	v_mul_f32_e32 v3, v8, v9
	v_cvt_pk_bf16_f32 v8, v0, v12
	v_cvt_pk_bf16_f32 v9, v10, v3
	ds_write_b64 v214, v[8:9] offset:48
	s_waitcnt vmcnt(11)
	v_mov_b32_e32 v8, v120
	v_mov_b32_e32 v9, v121
	v_mov_b32_e32 v10, v48
	v_lshlrev_b32_e32 v3, 16, v8
	v_mul_f32_e32 v0, 0xbfb8aa3b, v3
	v_exp_f32_e32 v0, v0
	s_nop 0
	v_add_f32_e32 v0, 1.0, v0
	v_rcp_f32_e32 v11, v0
	s_nop 0
	v_pk_mul_f32 v[10:11], v[10:11], v[2:3]
	v_and_b32_e32 v3, 0xffff0000, v8
	v_mul_f32_e32 v8, 0xbfb8aa3b, v3
	v_exp_f32_e32 v8, v8
	v_mul_f32_e32 v0, v10, v11
	v_mov_b32_e32 v10, v49
	v_add_f32_e32 v8, 1.0, v8
	v_rcp_f32_e32 v11, v8
	s_nop 0
	v_pk_mul_f32 v[10:11], v[10:11], v[2:3]
	v_lshlrev_b32_e32 v3, 16, v9
	v_mul_f32_e32 v8, 0xbfb8aa3b, v3
	v_exp_f32_e32 v8, v8
	v_mul_f32_e32 v12, v10, v11
	v_mov_b32_e32 v10, v50
	v_add_f32_e32 v8, 1.0, v8
	v_rcp_f32_e32 v11, v8
	s_nop 0
	v_pk_mul_f32 v[10:11], v[10:11], v[2:3]
	v_and_b32_e32 v3, 0xffff0000, v9
	v_mul_f32_e32 v8, 0xbfb8aa3b, v3
	v_exp_f32_e32 v8, v8
	v_mul_f32_e32 v10, v10, v11
	v_add_f32_e32 v8, 1.0, v8
	v_rcp_f32_e32 v9, v8
	v_mov_b32_e32 v8, v51
	v_pk_mul_f32 v[8:9], v[8:9], v[2:3]
	s_nop 0
	v_mul_f32_e32 v3, v8, v9
	v_cvt_pk_bf16_f32 v8, v0, v12
	v_cvt_pk_bf16_f32 v9, v10, v3
	ds_write_b64 v214, v[8:9] offset:64
	s_waitcnt vmcnt(10)
	v_mov_b32_e32 v8, v122
	v_mov_b32_e32 v9, v123
	v_mov_b32_e32 v10, v52
	v_lshlrev_b32_e32 v3, 16, v8
	v_mul_f32_e32 v0, 0xbfb8aa3b, v3
	v_exp_f32_e32 v0, v0
	s_nop 0
	v_add_f32_e32 v0, 1.0, v0
	v_rcp_f32_e32 v11, v0
	s_nop 0
	v_pk_mul_f32 v[10:11], v[10:11], v[2:3]
	v_and_b32_e32 v3, 0xffff0000, v8
	v_mul_f32_e32 v8, 0xbfb8aa3b, v3
	v_exp_f32_e32 v8, v8
	v_mul_f32_e32 v0, v10, v11
	v_mov_b32_e32 v10, v53
	v_add_f32_e32 v8, 1.0, v8
	v_rcp_f32_e32 v11, v8
	s_nop 0
	v_pk_mul_f32 v[10:11], v[10:11], v[2:3]
	v_lshlrev_b32_e32 v3, 16, v9
	v_mul_f32_e32 v8, 0xbfb8aa3b, v3
	v_exp_f32_e32 v8, v8
	v_mul_f32_e32 v12, v10, v11
	v_mov_b32_e32 v10, v54
	v_add_f32_e32 v8, 1.0, v8
	v_rcp_f32_e32 v11, v8
	s_nop 0
	v_pk_mul_f32 v[10:11], v[10:11], v[2:3]
	v_and_b32_e32 v3, 0xffff0000, v9
	v_mul_f32_e32 v8, 0xbfb8aa3b, v3
	v_exp_f32_e32 v8, v8
	v_mul_f32_e32 v10, v10, v11
	v_add_f32_e32 v8, 1.0, v8
	v_rcp_f32_e32 v9, v8
	v_mov_b32_e32 v8, v55
	v_pk_mul_f32 v[8:9], v[8:9], v[2:3]
	s_nop 0
	v_mul_f32_e32 v3, v8, v9
	v_cvt_pk_bf16_f32 v8, v0, v12
	v_cvt_pk_bf16_f32 v9, v10, v3
	ds_write_b64 v214, v[8:9] offset:80
	s_waitcnt vmcnt(9)
	v_mov_b32_e32 v8, v124
	v_mov_b32_e32 v9, v125
	v_mov_b32_e32 v10, v56
	v_lshlrev_b32_e32 v3, 16, v8
	v_mul_f32_e32 v0, 0xbfb8aa3b, v3
	v_exp_f32_e32 v0, v0
	s_nop 0
	v_add_f32_e32 v0, 1.0, v0
	v_rcp_f32_e32 v11, v0
	s_nop 0
	v_pk_mul_f32 v[10:11], v[10:11], v[2:3]
	v_and_b32_e32 v3, 0xffff0000, v8
	v_mul_f32_e32 v8, 0xbfb8aa3b, v3
	v_exp_f32_e32 v8, v8
	v_mul_f32_e32 v0, v10, v11
	v_mov_b32_e32 v10, v57
	v_add_f32_e32 v8, 1.0, v8
	v_rcp_f32_e32 v11, v8
	s_nop 0
	v_pk_mul_f32 v[10:11], v[10:11], v[2:3]
	v_lshlrev_b32_e32 v3, 16, v9
	v_mul_f32_e32 v8, 0xbfb8aa3b, v3
	v_exp_f32_e32 v8, v8
	v_mul_f32_e32 v12, v10, v11
	v_mov_b32_e32 v10, v58
	v_add_f32_e32 v8, 1.0, v8
	v_rcp_f32_e32 v11, v8
	s_nop 0
	v_pk_mul_f32 v[10:11], v[10:11], v[2:3]
	v_and_b32_e32 v3, 0xffff0000, v9
	v_mul_f32_e32 v8, 0xbfb8aa3b, v3
	v_exp_f32_e32 v8, v8
	v_mul_f32_e32 v10, v10, v11
	v_add_f32_e32 v8, 1.0, v8
	v_rcp_f32_e32 v9, v8
	v_mov_b32_e32 v8, v59
	v_pk_mul_f32 v[8:9], v[8:9], v[2:3]
	s_nop 0
	v_mul_f32_e32 v3, v8, v9
	v_cvt_pk_bf16_f32 v8, v0, v12
	v_cvt_pk_bf16_f32 v9, v10, v3
	ds_write_b64 v214, v[8:9] offset:96
	s_waitcnt vmcnt(8)
; __device__ __forceinline__ float bflo(unsigned w) { return __uint_as_float(w << 16); }
; __device__ __forceinline__ float bfhi(unsigned w) { return __uint_as_float(w & 0xffff0000u); }
; __device__ __forceinline__ unsigned cvtpk(float lo, float hi) { unsigned r; asm volatile("v_cvt_pk_bf16_f32 %0, %1, %2" : "=v"(r) : "v"(lo), "v"(hi)); return r; }
; __device__ __forceinline__ float siluf_(float x) { return x * sigmoidf_(x); }
; __device__ __forceinline__ void item_fox(const Params& p, int l, int bl, int h, int qb, LAS unsigned char* lds) {
;     ...
;       for (int db = 0; db < 4; ++db)
; #pragma unroll
;           for (int r4 = 0; r4 < 4; ++r4) {
;               const int d0 = 32 * db + 8 * r4 + 4 * hi; const u32x2 z = *(const u32x2*)(zp + d0);
;               const float o0 = O[db][4 * r4] * inv * siluf_(bflo(z[0])), o1 = O[db][4 * r4 + 1] * inv * siluf_(bfhi(z[0])),
;                           o2 = O[db][4 * r4 + 2] * inv * siluf_(bflo(z[1])), o3 = O[db][4 * r4 + 3] * inv * siluf_(bfhi(z[1]));
;               u32x2 o = {cvtpk(o0, o1), cvtpk(o2, o3)}; *(u32x2*)(yp + d0) = o; } }
	v_mov_b32_e32 v8, v126
	v_mov_b32_e32 v9, v127
	v_mov_b32_e32 v10, v60
	v_lshlrev_b32_e32 v3, 16, v8
	v_mul_f32_e32 v0, 0xbfb8aa3b, v3
	v_exp_f32_e32 v0, v0
	s_nop 0
	v_add_f32_e32 v0, 1.0, v0
	v_rcp_f32_e32 v11, v0
	s_nop 0
	v_pk_mul_f32 v[10:11], v[10:11], v[2:3]
	v_and_b32_e32 v3, 0xffff0000, v8
	v_mul_f32_e32 v8, 0xbfb8aa3b, v3
	v_exp_f32_e32 v8, v8
	v_mul_f32_e32 v0, v10, v11
	v_mov_b32_e32 v10, v61
	v_add_f32_e32 v8, 1.0, v8
	v_rcp_f32_e32 v11, v8
	s_nop 0
	v_pk_mul_f32 v[10:11], v[10:11], v[2:3]
	v_lshlrev_b32_e32 v3, 16, v9
	v_mul_f32_e32 v8, 0xbfb8aa3b, v3
	v_exp_f32_e32 v8, v8
	v_mul_f32_e32 v12, v10, v11
	v_mov_b32_e32 v10, v62
	v_add_f32_e32 v8, 1.0, v8
	v_rcp_f32_e32 v11, v8
	s_nop 0
	v_pk_mul_f32 v[10:11], v[10:11], v[2:3]
	v_and_b32_e32 v3, 0xffff0000, v9
	v_mul_f32_e32 v8, 0xbfb8aa3b, v3
	v_exp_f32_e32 v8, v8
	v_mul_f32_e32 v10, v10, v11
	v_add_f32_e32 v8, 1.0, v8
	v_rcp_f32_e32 v9, v8
	v_mov_b32_e32 v8, v63
	v_pk_mul_f32 v[8:9], v[8:9], v[2:3]
	s_nop 0
	v_mul_f32_e32 v3, v8, v9
	v_cvt_pk_bf16_f32 v8, v0, v12
	v_cvt_pk_bf16_f32 v9, v10, v3
	ds_write_b64 v214, v[8:9] offset:112
	s_waitcnt vmcnt(7)
	v_mov_b32_e32 v8, v128
	v_mov_b32_e32 v9, v129
	v_mov_b32_e32 v10, v32
	v_lshlrev_b32_e32 v3, 16, v8
	v_mul_f32_e32 v0, 0xbfb8aa3b, v3
	v_exp_f32_e32 v0, v0
	s_nop 0
	v_add_f32_e32 v0, 1.0, v0
	v_rcp_f32_e32 v11, v0
	s_nop 0
	v_pk_mul_f32 v[10:11], v[10:11], v[2:3]
	v_and_b32_e32 v3, 0xffff0000, v8
	v_mul_f32_e32 v8, 0xbfb8aa3b, v3
	v_exp_f32_e32 v8, v8
	v_mul_f32_e32 v0, v10, v11
	v_mov_b32_e32 v10, v33
	v_add_f32_e32 v8, 1.0, v8
	v_rcp_f32_e32 v11, v8
	s_nop 0
	v_pk_mul_f32 v[10:11], v[10:11], v[2:3]
	v_lshlrev_b32_e32 v3, 16, v9
	v_mul_f32_e32 v8, 0xbfb8aa3b, v3
	v_exp_f32_e32 v8, v8
	v_mul_f32_e32 v12, v10, v11
	v_mov_b32_e32 v10, v34
	v_add_f32_e32 v8, 1.0, v8
	v_rcp_f32_e32 v11, v8
	s_nop 0
	v_pk_mul_f32 v[10:11], v[10:11], v[2:3]
	v_and_b32_e32 v3, 0xffff0000, v9
	v_mul_f32_e32 v8, 0xbfb8aa3b, v3
	v_exp_f32_e32 v8, v8
	v_mul_f32_e32 v10, v10, v11
	v_add_f32_e32 v8, 1.0, v8
	v_rcp_f32_e32 v9, v8
	v_mov_b32_e32 v8, v35
	v_pk_mul_f32 v[8:9], v[8:9], v[2:3]
	s_nop 0
	v_mul_f32_e32 v3, v8, v9
	v_cvt_pk_bf16_f32 v8, v0, v12
	v_cvt_pk_bf16_f32 v9, v10, v3
	ds_write_b64 v214, v[8:9] offset:128
	s_waitcnt vmcnt(6)
	v_mov_b32_e32 v8, v130
	v_mov_b32_e32 v9, v131
	v_mov_b32_e32 v10, v36
	v_lshlrev_b32_e32 v3, 16, v8
	v_mul_f32_e32 v0, 0xbfb8aa3b, v3
	v_exp_f32_e32 v0, v0
	s_nop 0
	v_add_f32_e32 v0, 1.0, v0
	v_rcp_f32_e32 v11, v0
	s_nop 0
	v_pk_mul_f32 v[10:11], v[10:11], v[2:3]
	v_and_b32_e32 v3, 0xffff0000, v8
	v_mul_f32_e32 v8, 0xbfb8aa3b, v3
	v_exp_f32_e32 v8, v8
	v_mul_f32_e32 v0, v10, v11
	v_mov_b32_e32 v10, v37
	v_add_f32_e32 v8, 1.0, v8
	v_rcp_f32_e32 v11, v8
	s_nop 0
	v_pk_mul_f32 v[10:11], v[10:11], v[2:3]
	v_lshlrev_b32_e32 v3, 16, v9
	v_mul_f32_e32 v8, 0xbfb8aa3b, v3
	v_exp_f32_e32 v8, v8
	v_mul_f32_e32 v12, v10, v11
	v_mov_b32_e32 v10, v38
	v_add_f32_e32 v8, 1.0, v8
	v_rcp_f32_e32 v11, v8
	s_nop 0
	v_pk_mul_f32 v[10:11], v[10:11], v[2:3]
	v_and_b32_e32 v3, 0xffff0000, v9
	v_mul_f32_e32 v8, 0xbfb8aa3b, v3
	v_exp_f32_e32 v8, v8
	v_mul_f32_e32 v10, v10, v11
	v_add_f32_e32 v8, 1.0, v8
	v_rcp_f32_e32 v9, v8
	v_mov_b32_e32 v8, v39
	v_pk_mul_f32 v[8:9], v[8:9], v[2:3]
	s_nop 0
	v_mul_f32_e32 v3, v8, v9
	v_cvt_pk_bf16_f32 v8, v0, v12
	v_cvt_pk_bf16_f32 v9, v10, v3
	ds_write_b64 v214, v[8:9] offset:144
	s_waitcnt vmcnt(5)
	v_mov_b32_e32 v8, v132
	v_mov_b32_e32 v9, v133
	v_mov_b32_e32 v10, v40
	v_lshlrev_b32_e32 v3, 16, v8
	v_mul_f32_e32 v0, 0xbfb8aa3b, v3
	v_exp_f32_e32 v0, v0
	s_nop 0
	v_add_f32_e32 v0, 1.0, v0
	v_rcp_f32_e32 v11, v0
	s_nop 0
	v_pk_mul_f32 v[10:11], v[10:11], v[2:3]
	v_and_b32_e32 v3, 0xffff0000, v8
	v_mul_f32_e32 v8, 0xbfb8aa3b, v3
	v_exp_f32_e32 v8, v8
	v_mul_f32_e32 v0, v10, v11
	v_mov_b32_e32 v10, v41
	v_add_f32_e32 v8, 1.0, v8
	v_rcp_f32_e32 v11, v8
	s_nop 0
	v_pk_mul_f32 v[10:11], v[10:11], v[2:3]
	v_lshlrev_b32_e32 v3, 16, v9
	v_mul_f32_e32 v8, 0xbfb8aa3b, v3
	v_exp_f32_e32 v8, v8
	v_mul_f32_e32 v12, v10, v11
	v_mov_b32_e32 v10, v42
	v_add_f32_e32 v8, 1.0, v8
	v_rcp_f32_e32 v11, v8
	s_nop 0
	v_pk_mul_f32 v[10:11], v[10:11], v[2:3]
	v_and_b32_e32 v3, 0xffff0000, v9
	v_mul_f32_e32 v8, 0xbfb8aa3b, v3
	v_exp_f32_e32 v8, v8
	v_mul_f32_e32 v10, v10, v11
	v_add_f32_e32 v8, 1.0, v8
	v_rcp_f32_e32 v9, v8
	v_mov_b32_e32 v8, v43
	v_pk_mul_f32 v[8:9], v[8:9], v[2:3]
	s_nop 0
	v_mul_f32_e32 v3, v8, v9
	v_cvt_pk_bf16_f32 v8, v0, v12
	v_cvt_pk_bf16_f32 v9, v10, v3
	ds_write_b64 v214, v[8:9] offset:160
	s_waitcnt vmcnt(4)
	v_mov_b32_e32 v8, v134
	v_mov_b32_e32 v9, v135
	v_mov_b32_e32 v10, v44
	v_lshlrev_b32_e32 v3, 16, v8
	v_mul_f32_e32 v0, 0xbfb8aa3b, v3
	v_exp_f32_e32 v0, v0
	s_nop 0
	v_add_f32_e32 v0, 1.0, v0
	v_rcp_f32_e32 v11, v0
	s_nop 0
	v_pk_mul_f32 v[10:11], v[10:11], v[2:3]
	v_and_b32_e32 v3, 0xffff0000, v8
	v_mul_f32_e32 v8, 0xbfb8aa3b, v3
	v_exp_f32_e32 v8, v8
	v_mul_f32_e32 v0, v10, v11
	v_mov_b32_e32 v10, v45
	v_add_f32_e32 v8, 1.0, v8
	v_rcp_f32_e32 v11, v8
	s_nop 0
	v_pk_mul_f32 v[10:11], v[10:11], v[2:3]
	v_lshlrev_b32_e32 v3, 16, v9
	v_mul_f32_e32 v8, 0xbfb8aa3b, v3
	v_exp_f32_e32 v8, v8
	v_mul_f32_e32 v12, v10, v11
	v_mov_b32_e32 v10, v46
	v_add_f32_e32 v8, 1.0, v8
	v_rcp_f32_e32 v11, v8
	s_nop 0
	v_pk_mul_f32 v[10:11], v[10:11], v[2:3]
	v_and_b32_e32 v3, 0xffff0000, v9
	v_mul_f32_e32 v8, 0xbfb8aa3b, v3
	v_exp_f32_e32 v8, v8
	v_mul_f32_e32 v10, v10, v11
	v_add_f32_e32 v8, 1.0, v8
	v_rcp_f32_e32 v9, v8
	v_mov_b32_e32 v8, v47
	v_pk_mul_f32 v[8:9], v[8:9], v[2:3]
	s_nop 0
	v_mul_f32_e32 v3, v8, v9
	v_cvt_pk_bf16_f32 v8, v0, v12
	v_cvt_pk_bf16_f32 v9, v10, v3
	ds_write_b64 v214, v[8:9] offset:176
	s_waitcnt vmcnt(3)
; __device__ __forceinline__ float bflo(unsigned w) { return __uint_as_float(w << 16); }
; __device__ __forceinline__ float bfhi(unsigned w) { return __uint_as_float(w & 0xffff0000u); }
; __device__ __forceinline__ unsigned cvtpk(float lo, float hi) { unsigned r; asm volatile("v_cvt_pk_bf16_f32 %0, %1, %2" : "=v"(r) : "v"(lo), "v"(hi)); return r; }
; __device__ __forceinline__ float siluf_(float x) { return x * sigmoidf_(x); }
; __device__ __forceinline__ void item_fox(const Params& p, int l, int bl, int h, int qb, LAS unsigned char* lds) {
;     ...
;       for (int db = 0; db < 4; ++db)
; #pragma unroll
;           for (int r4 = 0; r4 < 4; ++r4) {
;               const int d0 = 32 * db + 8 * r4 + 4 * hi; const u32x2 z = *(const u32x2*)(zp + d0);
;               const float o0 = O[db][4 * r4] * inv * siluf_(bflo(z[0])), o1 = O[db][4 * r4 + 1] * inv * siluf_(bfhi(z[0])),
;                           o2 = O[db][4 * r4 + 2] * inv * siluf_(bflo(z[1])), o3 = O[db][4 * r4 + 3] * inv * siluf_(bfhi(z[1]));
;               u32x2 o = {cvtpk(o0, o1), cvtpk(o2, o3)}; *(u32x2*)(yp + d0) = o; } }
;     __syncthreads();
	v_mov_b32_e32 v8, v136
	v_mov_b32_e32 v9, v137
	v_mov_b32_e32 v10, v16
	v_lshlrev_b32_e32 v3, 16, v8
	v_mul_f32_e32 v0, 0xbfb8aa3b, v3
	v_exp_f32_e32 v0, v0
	s_nop 0
	v_add_f32_e32 v0, 1.0, v0
	v_rcp_f32_e32 v11, v0
	s_nop 0
	v_pk_mul_f32 v[10:11], v[10:11], v[2:3]
	v_and_b32_e32 v3, 0xffff0000, v8
	v_mul_f32_e32 v8, 0xbfb8aa3b, v3
	v_exp_f32_e32 v8, v8
	v_mul_f32_e32 v0, v10, v11
	v_mov_b32_e32 v10, v17
	v_add_f32_e32 v8, 1.0, v8
	v_rcp_f32_e32 v11, v8
	s_nop 0
	v_pk_mul_f32 v[10:11], v[10:11], v[2:3]
	v_lshlrev_b32_e32 v3, 16, v9
	v_mul_f32_e32 v8, 0xbfb8aa3b, v3
	v_exp_f32_e32 v8, v8
	v_mul_f32_e32 v12, v10, v11
	v_mov_b32_e32 v10, v18
	v_add_f32_e32 v8, 1.0, v8
	v_rcp_f32_e32 v11, v8
	s_nop 0
	v_pk_mul_f32 v[10:11], v[10:11], v[2:3]
	v_and_b32_e32 v3, 0xffff0000, v9
	v_mul_f32_e32 v8, 0xbfb8aa3b, v3
	v_exp_f32_e32 v8, v8
	v_mul_f32_e32 v10, v10, v11
	v_add_f32_e32 v8, 1.0, v8
	v_rcp_f32_e32 v9, v8
	v_mov_b32_e32 v8, v19
	v_pk_mul_f32 v[8:9], v[8:9], v[2:3]
	s_nop 0
	v_mul_f32_e32 v3, v8, v9
	v_cvt_pk_bf16_f32 v8, v0, v12
	v_cvt_pk_bf16_f32 v9, v10, v3
	ds_write_b64 v214, v[8:9] offset:192
	s_waitcnt vmcnt(2)
	v_mov_b32_e32 v8, v138
	v_mov_b32_e32 v9, v139
	v_mov_b32_e32 v10, v20
	v_lshlrev_b32_e32 v3, 16, v8
	v_mul_f32_e32 v0, 0xbfb8aa3b, v3
	v_exp_f32_e32 v0, v0
	s_nop 0
	v_add_f32_e32 v0, 1.0, v0
	v_rcp_f32_e32 v11, v0
	s_nop 0
	v_pk_mul_f32 v[10:11], v[10:11], v[2:3]
	v_and_b32_e32 v3, 0xffff0000, v8
	v_mul_f32_e32 v8, 0xbfb8aa3b, v3
	v_exp_f32_e32 v8, v8
	v_mul_f32_e32 v0, v10, v11
	v_mov_b32_e32 v10, v21
	v_add_f32_e32 v8, 1.0, v8
	v_rcp_f32_e32 v11, v8
	s_nop 0
	v_pk_mul_f32 v[10:11], v[10:11], v[2:3]
	v_lshlrev_b32_e32 v3, 16, v9
	v_mul_f32_e32 v8, 0xbfb8aa3b, v3
	v_exp_f32_e32 v8, v8
	v_mul_f32_e32 v12, v10, v11
	v_mov_b32_e32 v10, v22
	v_add_f32_e32 v8, 1.0, v8
	v_rcp_f32_e32 v11, v8
	s_nop 0
	v_pk_mul_f32 v[10:11], v[10:11], v[2:3]
	v_and_b32_e32 v3, 0xffff0000, v9
	v_mul_f32_e32 v8, 0xbfb8aa3b, v3
	v_exp_f32_e32 v8, v8
	v_mul_f32_e32 v10, v10, v11
	v_add_f32_e32 v8, 1.0, v8
	v_rcp_f32_e32 v9, v8
	v_mov_b32_e32 v8, v23
	v_pk_mul_f32 v[8:9], v[8:9], v[2:3]
	s_nop 0
	v_mul_f32_e32 v3, v8, v9
	v_cvt_pk_bf16_f32 v8, v0, v12
	v_cvt_pk_bf16_f32 v9, v10, v3
	ds_write_b64 v214, v[8:9] offset:208
	s_waitcnt vmcnt(1)
	v_mov_b32_e32 v8, v140
	v_mov_b32_e32 v9, v141
	v_mov_b32_e32 v10, v24
	v_lshlrev_b32_e32 v3, 16, v8
	v_mul_f32_e32 v0, 0xbfb8aa3b, v3
	v_exp_f32_e32 v0, v0
	s_nop 0
	v_add_f32_e32 v0, 1.0, v0
	v_rcp_f32_e32 v11, v0
	s_nop 0
	v_pk_mul_f32 v[10:11], v[10:11], v[2:3]
	v_and_b32_e32 v3, 0xffff0000, v8
	v_mul_f32_e32 v8, 0xbfb8aa3b, v3
	v_exp_f32_e32 v8, v8
	v_mul_f32_e32 v0, v10, v11
	v_mov_b32_e32 v10, v25
	v_add_f32_e32 v8, 1.0, v8
	v_rcp_f32_e32 v11, v8
	s_nop 0
	v_pk_mul_f32 v[10:11], v[10:11], v[2:3]
	v_lshlrev_b32_e32 v3, 16, v9
	v_mul_f32_e32 v8, 0xbfb8aa3b, v3
	v_exp_f32_e32 v8, v8
	v_mul_f32_e32 v12, v10, v11
	v_mov_b32_e32 v10, v26
	v_add_f32_e32 v8, 1.0, v8
	v_rcp_f32_e32 v11, v8
	s_nop 0
	v_pk_mul_f32 v[10:11], v[10:11], v[2:3]
	v_and_b32_e32 v3, 0xffff0000, v9
	v_mul_f32_e32 v8, 0xbfb8aa3b, v3
	v_exp_f32_e32 v8, v8
	v_mul_f32_e32 v10, v10, v11
	v_add_f32_e32 v8, 1.0, v8
	v_rcp_f32_e32 v9, v8
	v_mov_b32_e32 v8, v27
	v_pk_mul_f32 v[8:9], v[8:9], v[2:3]
	s_nop 0
	v_mul_f32_e32 v3, v8, v9
	v_cvt_pk_bf16_f32 v8, v0, v12
	v_cvt_pk_bf16_f32 v9, v10, v3
	ds_write_b64 v214, v[8:9] offset:224
	s_waitcnt vmcnt(0)
	v_mov_b32_e32 v4, v142
	v_mov_b32_e32 v5, v143
	v_mov_b32_e32 v8, v28
	v_lshlrev_b32_e32 v3, 16, v4
	v_mul_f32_e32 v0, 0xbfb8aa3b, v3
	v_exp_f32_e32 v0, v0
	s_nop 0
	v_add_f32_e32 v0, 1.0, v0
	v_rcp_f32_e32 v9, v0
	s_nop 0
	v_pk_mul_f32 v[8:9], v[8:9], v[2:3]
	v_and_b32_e32 v3, 0xffff0000, v4
	v_mul_f32_e32 v4, 0xbfb8aa3b, v3
	v_exp_f32_e32 v4, v4
	v_mul_f32_e32 v0, v8, v9
	v_mov_b32_e32 v8, v29
	v_add_f32_e32 v4, 1.0, v4
	v_rcp_f32_e32 v9, v4
	s_nop 0
	v_pk_mul_f32 v[8:9], v[8:9], v[2:3]
	v_lshlrev_b32_e32 v3, 16, v5
	v_mul_f32_e32 v4, 0xbfb8aa3b, v3
	v_exp_f32_e32 v4, v4
	v_mul_f32_e32 v10, v8, v9
	v_mov_b32_e32 v8, v30
	v_add_f32_e32 v4, 1.0, v4
	v_rcp_f32_e32 v9, v4
	s_nop 0
	v_pk_mul_f32 v[8:9], v[8:9], v[2:3]
	v_and_b32_e32 v3, 0xffff0000, v5
	v_mul_f32_e32 v4, 0xbfb8aa3b, v3
	v_exp_f32_e32 v4, v4
	v_mul_f32_e32 v8, v8, v9
	v_add_f32_e32 v4, 1.0, v4
	v_rcp_f32_e32 v5, v4
	v_mov_b32_e32 v4, v31
	v_pk_mul_f32 v[2:3], v[4:5], v[2:3]
	s_nop 0
	v_mul_f32_e32 v3, v2, v3
	v_cvt_pk_bf16_f32 v2, v0, v10
	v_cvt_pk_bf16_f32 v3, v8, v3
	ds_write_b64 v214, v[2:3] offset:240
	s_waitcnt lgkmcnt(0)
	ds_read_b128 v[80:83], v215
	ds_read_b128 v[84:87], v215 offset:1088
	ds_read_b128 v[88:91], v215 offset:2176
	ds_read_b128 v[92:95], v215 offset:3264
	ds_read_b128 v[96:99], v215 offset:4352
	ds_read_b128 v[100:103], v215 offset:5440
	ds_read_b128 v[104:107], v215 offset:6528
	ds_read_b128 v[108:111], v215 offset:7616
	s_waitcnt lgkmcnt(7)
	global_store_dwordx4 v[212:213], v[80:83], off
	s_waitcnt lgkmcnt(6)
	s_mov_b64 s[20:21], 0x1000
	v_lshl_add_u64 v[216:217], v[212:213], 0, s[20:21]
	global_store_dwordx4 v[216:217], v[84:87], off
	s_waitcnt lgkmcnt(5)
	s_mov_b64 s[20:21], 0x2000
	v_lshl_add_u64 v[218:219], v[212:213], 0, s[20:21]
	global_store_dwordx4 v[218:219], v[88:91], off
	s_waitcnt lgkmcnt(4)
	s_mov_b64 s[20:21], 0x3000
	v_lshl_add_u64 v[216:217], v[212:213], 0, s[20:21]
	global_store_dwordx4 v[216:217], v[92:95], off
	s_waitcnt lgkmcnt(3)
	s_mov_b64 s[20:21], 0x4000
	v_lshl_add_u64 v[218:219], v[212:213], 0, s[20:21]
	global_store_dwordx4 v[218:219], v[96:99], off
	s_waitcnt lgkmcnt(2)
	s_mov_b64 s[20:21], 0x5000
	v_lshl_add_u64 v[216:217], v[212:213], 0, s[20:21]
	global_store_dwordx4 v[216:217], v[100:103], off
	s_waitcnt lgkmcnt(1)
	s_mov_b64 s[20:21], 0x6000
	v_lshl_add_u64 v[218:219], v[212:213], 0, s[20:21]
	global_store_dwordx4 v[218:219], v[104:107], off
	s_waitcnt lgkmcnt(0)
	s_mov_b64 s[20:21], 0x7000
	v_lshl_add_u64 v[216:217], v[212:213], 0, s[20:21]
	global_store_dwordx4 v[216:217], v[108:111], off
	s_barrier
